# retention-state units: no drain of the previous unit's stores before the workgroup barrier (the counted load waits that follow already cover them in order)
# speedup vs baseline: 1.0032x; 1.0032x over previous
; #define LAS __attribute__((address_space(3)))
; __device__ __forceinline__ float bflo(unsigned w) { return __uint_as_float(w << 16); }
; __device__ __forceinline__ void retkv_mfma_unit(unsigned char* ws, LAS unsigned char* lds, int u, const int tid) {
;     const int b = u >> 7, h = (u >> 5) & 3, n = u & 31;
;     const int lane = tid & 63, w = __builtin_amdgcn_readfirstlane(tid >> 6), fr = lane & 15, fq = lane >> 4;
;     const bf16_t* RK = (const bf16_t*)(ws + WS_R + R_RK); const bf16_t* RV = (const bf16_t*)(ws + WS_R + R_RV);
;     const float lg2 = log2f(1.f - exp2f(-5.f - (float)h));
;     const size_t row0 = (size_t)b * SEQ + n * 128;
;     LAS bf16_t* VT = (LAS bf16_t*)lds; LAS bf16_t* KT = VT + 64 * RP128;
;     __syncthreads();
;     { const int r = tid >> 2, c0 = (tid & 3) * 16;
;       const u32x4* vs = (const u32x4*)(RV + (row0 + r) * 256 + h * 64 + c0); const u32x4 a0 = vs[0], a1 = vs[1];
;       const u32x4* ksrc = (const u32x4*)(RK + (row0 + r) * 256 + h * 64 + c0); const u32x4 k0 = ksrc[0], k1 = ksrc[1];
;       const unsigned vw[8] = {a0.x, a0.y, a0.z, a0.w, a1.x, a1.y, a1.z, a1.w}; const unsigned kw[8] = {k0.x, k0.y, k0.z, k0.w, k1.x, k1.y, k1.z, k1.w};
;       const float dec = exp2f(lg2 * (float)(127 - r));
; #pragma unroll
;       for (int i = 0; i < 8; ++i) { VT[(c0 + 2 * i) * RP128 + r] = (bf16_t)(vw[i] & 0xffffu); VT[(c0 + 2 * i + 1) * RP128 + r] = (bf16_t)(vw[i] >> 16);
;           const unsigned kp = cvt_pk_bf16(bflo(kw[i]) * dec, bfhi(kw[i]) * dec);
;           KT[(c0 + 2 * i) * RP128 + r] = (bf16_t)(kp & 0xffffu); KT[(c0 + 2 * i + 1) * RP128 + r] = (bf16_t)(kp >> 16); } }
;     __syncthreads();
;     const int et = w >> 1;
; #pragma unroll
;     for (int t2 = 0; t2 < 2; ++t2) { const int dt = (w & 1) * 2 + t2; f32x4 acc = (f32x4){0.f, 0.f, 0.f, 0.f};
; #pragma unroll
;         for (int sb = 0; sb < 4; ++sb) { const bf16x8 kf = *(const LAS bf16x8*)(KT + (16 * dt + fr) * RP128 + 32 * sb + 8 * fq); const bf16x8 vf = *(const LAS bf16x8*)(VT + (16 * et + fr) * RP128 + 32 * sb + 8 * fq);
;             acc = __builtin_amdgcn_mfma_f32_16x16x32_bf16(kf, vf, acc, 0, 0, 0); }
;         u32x2 o; o.x = cvtpk_c(acc[0], acc[1]); o.y = cvtpk_c(acc[2], acc[3]);
;         *(u32x2*)((bf16_t*)(ws + WS_KV) + (size_t)u * 4096 + (16 * et + fr) * 64 + 16 * dt + 4 * fq) = o; }
; }
.LBB0_214:
	s_bfe_u32 s11, s4, 0x20005
	v_cvt_f32_ubyte0_e32 v2, s11
	v_sub_f32_e32 v2, 0xc0a00000, v2
	v_cmp_gt_f32_e32 vcc, s87, v2
	s_ashr_i32 s18, s4, 7
	s_and_b64 s[22:23], vcc, exec
	v_cndmask_b32_e32 v3, 0, v189, vcc
	v_add_f32_e32 v2, v2, v3
	v_exp_f32_e32 v2, v2
	s_cselect_b32 s19, 0xffffffc0, 0
	v_readfirstlane_b32 s10, v164
	v_ldexp_f32 v2, v2, s19
	v_sub_f32_e32 v2, 1.0, v2
	v_cmp_gt_f32_e32 vcc, s74, v2
	s_and_b64 s[22:23], vcc, exec
	s_cselect_b32 s22, 32, 0
	s_and_b32 s28, s5, 0xf80
	s_ashr_i32 s19, s18, 31
	v_ldexp_f32 v4, v2, s22
	v_lshl_add_u64 v[2:3], s[28:29], 0, v[14:15]
	s_ashr_i32 s21, s10, 7
	s_lshr_b32 s23, s10, 1
	s_lshl_b64 s[18:19], s[18:19], 20
	v_lshlrev_b64 v[2:3], 8, v[2:3]
	s_lshl_b32 s28, s11, 7
	v_lshl_or_b32 v5, s21, 4, v25
	s_and_b32 s11, s23, 32
	v_lshl_add_u64 v[2:3], v[2:3], 0, s[18:19]
	v_log_f32_e32 v7, v4
	v_mad_u64_u32 v[22:23], s[22:23], v5, s83, v[16:17]
	v_or_b32_e32 v4, s11, v25
	v_or_b32_e32 v5, s11, v27
	v_lshlrev_b64 v[2:3], 1, v[2:3]
	v_mad_u32_u24 v20, v4, s83, v16
	v_mad_u32_u24 v23, v5, s83, v16
	v_lshl_add_u64 v[4:5], s[14:15], 0, v[2:3]
	v_lshl_add_u64 v[2:3], s[12:13], 0, v[2:3]
	v_lshl_add_u64 v[4:5], v[4:5], 0, s[28:29]
	v_lshl_add_u64 v[2:3], v[2:3], 0, s[28:29]
	v_cndmask_b32_e32 v6, 0, v190, vcc
	v_lshl_add_u64 v[28:29], v[4:5], 0, v[0:1]
	v_lshl_add_u64 v[10:11], v[2:3], 0, v[0:1]
	s_barrier
	v_sub_f32_e32 v32, v7, v6
	global_load_dwordx4 v[2:5], v[28:29], off
	global_load_dwordx4 v[6:9], v[10:11], off
	s_nop 0
	global_load_dwordx4 v[10:13], v[10:11], off offset:16
	s_nop 0
	global_load_dwordx4 v[28:31], v[28:29], off offset:16
	v_mul_f32_e32 v33, v32, v17
	v_cmp_gt_f32_e32 vcc, s87, v33
	s_and_b32 s10, s10, 64
	v_mov_b32_e32 v21, v1
	v_cndmask_b32_e32 v33, 0, v189, vcc
	v_fmac_f32_e32 v33, v32, v17
	v_exp_f32_e32 v33, v33
	v_cndmask_b32_e32 v32, 0, v191, vcc
	s_add_i32 s4, s4, s6
	s_add_i32 s5, s5, s7
	v_ldexp_f32 v32, v33, v32
	s_cmpk_gt_i32 s4, 0x3ff
	s_waitcnt vmcnt(3)
	ds_write_b16 v24, v2
	ds_write_b16_d16_hi v24, v2 offset:272
	s_waitcnt vmcnt(2)
	v_lshlrev_b32_e32 v2, 16, v6
	v_and_b32_e32 v6, 0xffff0000, v6
	v_mul_f32_e32 v2, v32, v2
	v_lshlrev_b32_e32 v33, 16, v7
	v_and_b32_e32 v7, 0xffff0000, v7
	v_mul_f32_e32 v6, v32, v6
	v_cvt_pk_bf16_f32 v2, v2, v6
	v_lshlrev_b32_e32 v34, 16, v8
	v_and_b32_e32 v8, 0xffff0000, v8
	v_mul_f32_e32 v33, v32, v33
	v_mul_f32_e32 v7, v32, v7
	ds_write_b16 v24, v3 offset:544
	ds_write_b16_d16_hi v24, v3 offset:816
	ds_write_b16 v24, v2 offset:17408
	ds_write_b16_d16_hi v24, v2 offset:17680
	v_cvt_pk_bf16_f32 v2, v33, v7
	v_lshlrev_b32_e32 v35, 16, v9
	v_and_b32_e32 v9, 0xffff0000, v9
	v_mul_f32_e32 v34, v32, v34
	v_mul_f32_e32 v8, v32, v8
	ds_write_b16 v24, v4 offset:1088
	ds_write_b16_d16_hi v24, v4 offset:1360
	ds_write_b16 v24, v2 offset:17952
	ds_write_b16_d16_hi v24, v2 offset:18224
	v_cvt_pk_bf16_f32 v2, v34, v8
	s_waitcnt vmcnt(1)
	v_lshlrev_b32_e32 v36, 16, v10
	v_and_b32_e32 v10, 0xffff0000, v10
	v_mul_f32_e32 v35, v32, v35
	v_mul_f32_e32 v9, v32, v9
	ds_write_b16 v24, v5 offset:1632
	ds_write_b16_d16_hi v24, v5 offset:1904
	ds_write_b16 v24, v2 offset:18496
	ds_write_b16_d16_hi v24, v2 offset:18768
	v_cvt_pk_bf16_f32 v2, v35, v9
	v_lshlrev_b32_e32 v37, 16, v11
	v_and_b32_e32 v11, 0xffff0000, v11
	v_mul_f32_e32 v36, v32, v36
	v_mul_f32_e32 v10, v32, v10
	s_waitcnt vmcnt(0)
	ds_write_b16 v24, v28 offset:2176
	ds_write_b16_d16_hi v24, v28 offset:2448
	ds_write_b16 v24, v2 offset:19040
	ds_write_b16_d16_hi v24, v2 offset:19312
	v_cvt_pk_bf16_f32 v2, v36, v10
	v_lshlrev_b32_e32 v38, 16, v12
	v_and_b32_e32 v12, 0xffff0000, v12
	v_mul_f32_e32 v37, v32, v37
	v_mul_f32_e32 v11, v32, v11
	ds_write_b16 v24, v29 offset:2720
	ds_write_b16_d16_hi v24, v29 offset:2992
	ds_write_b16 v24, v2 offset:19584
	ds_write_b16_d16_hi v24, v2 offset:19856
	v_cvt_pk_bf16_f32 v2, v37, v11
	v_lshlrev_b32_e32 v39, 16, v13
	v_and_b32_e32 v13, 0xffff0000, v13
	v_mul_f32_e32 v38, v32, v38
	v_mul_f32_e32 v12, v32, v12
	ds_write_b16 v24, v30 offset:3264
	ds_write_b16_d16_hi v24, v30 offset:3536
	ds_write_b16 v24, v2 offset:20128
	ds_write_b16_d16_hi v24, v2 offset:20400
	v_cvt_pk_bf16_f32 v2, v38, v12
	v_mul_f32_e32 v39, v32, v39
	v_mul_f32_e32 v13, v32, v13
	ds_write_b16 v24, v31 offset:3808
	ds_write_b16_d16_hi v24, v31 offset:4080
	ds_write_b16 v24, v2 offset:20672
	ds_write_b16_d16_hi v24, v2 offset:20944
	v_cvt_pk_bf16_f32 v2, v39, v13
	ds_write_b16 v24, v2 offset:21216
	ds_write_b16_d16_hi v24, v2 offset:21488
	s_waitcnt lgkmcnt(0)
	s_barrier
	ds_read_b128 v[10:13], v20 offset:17408
	ds_read_b128 v[28:31], v22
	ds_read_b128 v[6:9], v20 offset:17472
	ds_read_b128 v[2:5], v22 offset:64
	s_waitcnt lgkmcnt(2)
	v_mfma_f32_16x16x32_bf16 v[10:13], v[10:13], v[28:31], 0
	ds_read_b128 v[32:35], v23 offset:17408
	ds_read_b128 v[36:39], v23 offset:17472
	s_waitcnt lgkmcnt(2)
	v_mfma_f32_16x16x32_bf16 v[6:9], v[6:9], v[2:5], v[10:13]
	s_nop 3
	ds_read_b128 v[10:13], v20 offset:17536
	s_waitcnt lgkmcnt(2)
	v_mfma_f32_16x16x32_bf16 v[28:31], v[32:35], v[28:31], 0
	s_waitcnt lgkmcnt(1)
	v_mfma_f32_16x16x32_bf16 v[2:5], v[36:39], v[2:5], v[28:31]
	s_nop 5
	ds_read_b128 v[28:31], v22 offset:128
	ds_read_b128 v[32:35], v20 offset:17600
	ds_read_b128 v[36:39], v22 offset:192
	ds_read_b128 v[40:43], v23 offset:17600
	v_mov_b32_e32 v20, s10
	s_waitcnt lgkmcnt(3)
	v_mfma_f32_16x16x32_bf16 v[6:9], v[10:13], v[28:31], v[6:9]
	ds_read_b128 v[10:13], v23 offset:17536
	s_waitcnt lgkmcnt(0)
	v_mfma_f32_16x16x32_bf16 v[2:5], v[10:13], v[28:31], v[2:5]
	v_lshl_or_b32 v10, s21, 10, v26
	v_ashrrev_i32_e32 v11, 31, v10
	v_lshl_add_u64 v[10:11], v[10:11], 1, v[20:21]
	v_mfma_f32_16x16x32_bf16 v[6:9], v[32:35], v[36:39], v[6:9]
	v_lshl_add_u64 v[10:11], v[18:19], 0, v[10:11]
	v_lshl_add_u64 v[18:19], v[18:19], 0, s[8:9]
	v_mfma_f32_16x16x32_bf16 v[2:5], v[40:43], v[36:39], v[2:5]
	s_nop 4
	v_cvt_pk_bf16_f32 v6, v6, v7
	v_cvt_pk_bf16_f32 v7, v8, v9
	s_nop 0
	v_cvt_pk_bf16_f32 v2, v2, v3
	v_cvt_pk_bf16_f32 v3, v4, v5
	global_store_dwordx2 v[10:11], v[6:7], off offset:-32
	global_store_dwordx2 v[10:11], v[2:3], off
	s_cbranch_scc0 .LBB0_214
